# v58 + nt on the mLSTM output, attention output (MIXB) and final output stores (consumed by a later phase or never re-read)
# speedup vs baseline: 1.0117x; 1.0117x over previous
.LBB0_506:
	s_or_b64 exec, exec, s[36:37]
	s_waitcnt lgkmcnt(0)
	ds_read_b128 v[72:75], v173
	ds_read_b128 v[84:87], v173 offset:6400
	ds_read_b128 v[184:187], v173 offset:12800
	ds_read_b128 v[196:199], v173 offset:19200
	s_mul_i32 s36, s63, 0x60
	s_mulk_i32 s63, 0xc0
	s_lshl_b32 s37, s65, 6
	s_add_i32 s62, s62, s90
	s_waitcnt lgkmcnt(3)
	v_mfma_f32_16x16x32_bf16 v[76:79], v[72:75], v[60:63], 0
	v_mfma_f32_16x16x32_bf16 v[80:83], v[72:75], v[64:67], 0
	v_mfma_f32_16x16x32_bf16 v[72:75], v[72:75], v[68:71], 0
	s_waitcnt lgkmcnt(2)
	v_mfma_f32_16x16x32_bf16 v[176:179], v[84:87], v[60:63], 0
	v_mfma_f32_16x16x32_bf16 v[180:183], v[84:87], v[64:67], 0
	v_mfma_f32_16x16x32_bf16 v[84:87], v[84:87], v[68:71], 0
	s_waitcnt lgkmcnt(1)
	v_mfma_f32_16x16x32_bf16 v[188:191], v[184:187], v[60:63], 0
	v_mfma_f32_16x16x32_bf16 v[192:195], v[184:187], v[64:67], 0
	v_mfma_f32_16x16x32_bf16 v[184:187], v[184:187], v[68:71], 0
	s_waitcnt lgkmcnt(0)
	v_mfma_f32_16x16x32_bf16 v[60:63], v[196:199], v[60:63], 0
	v_mfma_f32_16x16x32_bf16 v[64:67], v[196:199], v[64:67], 0
	v_mfma_f32_16x16x32_bf16 v[68:71], v[196:199], v[68:71], 0
	ds_read_b128 v[196:199], v173 offset:64
	s_waitcnt lgkmcnt(0)
	v_mfma_f32_16x16x32_bf16 v[76:79], v[196:199], v[48:51], v[76:79]
	v_mfma_f32_16x16x32_bf16 v[80:83], v[196:199], v[52:55], v[80:83]
	v_mfma_f32_16x16x32_bf16 v[72:75], v[196:199], v[56:59], v[72:75]
	ds_read_b128 v[196:199], v173 offset:6464
	s_waitcnt lgkmcnt(0)
	v_mfma_f32_16x16x32_bf16 v[176:179], v[196:199], v[48:51], v[176:179]
	v_mfma_f32_16x16x32_bf16 v[180:183], v[196:199], v[52:55], v[180:183]
	v_mfma_f32_16x16x32_bf16 v[84:87], v[196:199], v[56:59], v[84:87]
	ds_read_b128 v[196:199], v173 offset:12864
	s_waitcnt lgkmcnt(0)
	v_mfma_f32_16x16x32_bf16 v[188:191], v[196:199], v[48:51], v[188:191]
	v_mfma_f32_16x16x32_bf16 v[192:195], v[196:199], v[52:55], v[192:195]
	v_mfma_f32_16x16x32_bf16 v[184:187], v[196:199], v[56:59], v[184:187]
	ds_read_b128 v[196:199], v173 offset:19264
	s_waitcnt lgkmcnt(0)
	v_mfma_f32_16x16x32_bf16 v[48:51], v[196:199], v[48:51], v[60:63]
	s_nop 2
	ds_read_b128 v[60:63], v173 offset:128
	v_mfma_f32_16x16x32_bf16 v[52:55], v[196:199], v[52:55], v[64:67]
	v_mfma_f32_16x16x32_bf16 v[56:59], v[196:199], v[56:59], v[68:71]
	s_waitcnt lgkmcnt(0)
	v_mfma_f32_16x16x32_bf16 v[64:67], v[60:63], v[36:39], v[76:79]
	v_mfma_f32_16x16x32_bf16 v[68:71], v[60:63], v[40:43], v[80:83]
	v_mfma_f32_16x16x32_bf16 v[60:63], v[60:63], v[44:47], v[72:75]
	s_nop 2
	ds_read_b128 v[72:75], v173 offset:6528
	s_waitcnt lgkmcnt(0)
	v_mfma_f32_16x16x32_bf16 v[76:79], v[72:75], v[36:39], v[176:179]
	v_mfma_f32_16x16x32_bf16 v[80:83], v[72:75], v[40:43], v[180:183]
	v_mfma_f32_16x16x32_bf16 v[72:75], v[72:75], v[44:47], v[84:87]
	s_nop 2
	ds_read_b128 v[84:87], v173 offset:12928
	s_waitcnt lgkmcnt(0)
	v_mfma_f32_16x16x32_bf16 v[176:179], v[84:87], v[36:39], v[188:191]
	v_mfma_f32_16x16x32_bf16 v[180:183], v[84:87], v[40:43], v[192:195]
	v_mfma_f32_16x16x32_bf16 v[84:87], v[84:87], v[44:47], v[184:187]
	s_nop 2
	ds_read_b128 v[184:187], v173 offset:19328
	s_waitcnt lgkmcnt(0)
	v_mfma_f32_16x16x32_bf16 v[36:39], v[184:187], v[36:39], v[48:51]
	s_nop 2
	ds_read_b128 v[48:51], v173 offset:192
	v_mfma_f32_16x16x32_bf16 v[40:43], v[184:187], v[40:43], v[52:55]
	v_mfma_f32_16x16x32_bf16 v[44:47], v[184:187], v[44:47], v[56:59]
	s_waitcnt lgkmcnt(0)
	v_mfma_f32_16x16x32_bf16 v[52:55], v[48:51], v[24:27], v[64:67]
	v_mfma_f32_16x16x32_bf16 v[56:59], v[48:51], v[28:31], v[68:71]
	v_mfma_f32_16x16x32_bf16 v[48:51], v[48:51], v[32:35], v[60:63]
	s_nop 2
	ds_read_b128 v[60:63], v173 offset:6592
	s_waitcnt lgkmcnt(0)
	v_mfma_f32_16x16x32_bf16 v[64:67], v[60:63], v[24:27], v[76:79]
	v_mfma_f32_16x16x32_bf16 v[68:71], v[60:63], v[28:31], v[80:83]
	v_mfma_f32_16x16x32_bf16 v[60:63], v[60:63], v[32:35], v[72:75]
	s_nop 2
	ds_read_b128 v[72:75], v173 offset:12992
	s_waitcnt lgkmcnt(0)
	v_mfma_f32_16x16x32_bf16 v[76:79], v[72:75], v[24:27], v[176:179]
	v_mfma_f32_16x16x32_bf16 v[80:83], v[72:75], v[28:31], v[180:183]
	v_mfma_f32_16x16x32_bf16 v[72:75], v[72:75], v[32:35], v[84:87]
	s_nop 2
	ds_read_b128 v[84:87], v173 offset:19392
	s_waitcnt lgkmcnt(0)
	v_mfma_f32_16x16x32_bf16 v[24:27], v[84:87], v[24:27], v[36:39]
	s_nop 2
	ds_read_b128 v[36:39], v173 offset:256
	v_mfma_f32_16x16x32_bf16 v[28:31], v[84:87], v[28:31], v[40:43]
	v_mfma_f32_16x16x32_bf16 v[32:35], v[84:87], v[32:35], v[44:47]
	s_waitcnt lgkmcnt(0)
	v_mfma_f32_16x16x32_bf16 v[40:43], v[36:39], v[12:15], v[52:55]
	v_mfma_f32_16x16x32_bf16 v[44:47], v[36:39], v[16:19], v[56:59]
	v_mfma_f32_16x16x32_bf16 v[36:39], v[36:39], v[20:23], v[48:51]
	s_nop 2
	ds_read_b128 v[48:51], v173 offset:6656
	s_waitcnt lgkmcnt(0)
	v_mfma_f32_16x16x32_bf16 v[52:55], v[48:51], v[12:15], v[64:67]
	v_mfma_f32_16x16x32_bf16 v[56:59], v[48:51], v[16:19], v[68:71]
	v_mfma_f32_16x16x32_bf16 v[48:51], v[48:51], v[20:23], v[60:63]
	s_nop 2
	ds_read_b128 v[60:63], v173 offset:13056
	s_waitcnt lgkmcnt(0)
	v_mfma_f32_16x16x32_bf16 v[64:67], v[60:63], v[12:15], v[76:79]
	v_mfma_f32_16x16x32_bf16 v[68:71], v[60:63], v[16:19], v[80:83]
	v_mfma_f32_16x16x32_bf16 v[60:63], v[60:63], v[20:23], v[72:75]
	s_nop 2
	ds_read_b128 v[72:75], v173 offset:19456
	s_waitcnt lgkmcnt(0)
	v_mfma_f32_16x16x32_bf16 v[12:15], v[72:75], v[12:15], v[24:27]
	s_nop 2
	ds_read_b128 v[24:27], v173 offset:320
	v_mfma_f32_16x16x32_bf16 v[16:19], v[72:75], v[16:19], v[28:31]
	v_mfma_f32_16x16x32_bf16 v[20:23], v[72:75], v[20:23], v[32:35]
	s_waitcnt lgkmcnt(0)
	v_mfma_f32_16x16x32_bf16 v[28:31], v[24:27], v[0:3], v[40:43]
	v_mfma_f32_16x16x32_bf16 v[32:35], v[24:27], v[4:7], v[44:47]
	v_mfma_f32_16x16x32_bf16 v[24:27], v[24:27], v[8:11], v[36:39]
	s_nop 2
	ds_read_b128 v[36:39], v173 offset:6720
	s_waitcnt lgkmcnt(0)
	v_mfma_f32_16x16x32_bf16 v[40:43], v[36:39], v[0:3], v[52:55]
	v_mfma_f32_16x16x32_bf16 v[44:47], v[36:39], v[4:7], v[56:59]
	v_mfma_f32_16x16x32_bf16 v[36:39], v[36:39], v[8:11], v[48:51]
	s_nop 2
	ds_read_b128 v[48:51], v173 offset:13120
	s_waitcnt lgkmcnt(0)
	v_mfma_f32_16x16x32_bf16 v[52:55], v[48:51], v[0:3], v[64:67]
	v_mfma_f32_16x16x32_bf16 v[56:59], v[48:51], v[4:7], v[68:71]
	v_mfma_f32_16x16x32_bf16 v[48:51], v[48:51], v[8:11], v[60:63]
	s_nop 1
	v_add_u32_e32 v68, s36, v141
	v_lshl_add_u32 v69, s64, 5, v141
	v_lshl_add_u32 v70, s65, 5, v141
	ds_read_b128 v[60:63], v173 offset:19520
	s_waitcnt lgkmcnt(0)
	v_mfma_f32_16x16x32_bf16 v[0:3], v[60:63], v[0:3], v[12:15]
	s_nop 2
	ds_read_b128 v[12:15], v94 offset:60928
	s_lshl_b32 s36, s64, 6
	s_cmpk_lt_i32 s62, 0x400
	v_mfma_f32_16x16x32_bf16 v[4:7], v[60:63], v[4:7], v[16:19]
	v_mfma_f32_16x16x32_bf16 v[8:11], v[60:63], v[8:11], v[20:23]
	s_waitcnt lgkmcnt(0)
	s_nop 0
	v_pk_mul_f32 v[18:19], v[30:31], v[14:15]
	v_pk_mul_f32 v[16:17], v[28:29], v[12:13]
	v_pk_mul_f32 v[22:23], v[34:35], v[14:15]
	v_pk_mul_f32 v[20:21], v[32:33], v[12:13]
	v_pk_mul_f32 v[14:15], v[26:27], v[14:15]
	v_pk_mul_f32 v[12:13], v[24:25], v[12:13]
	ds_read_b128 v[24:27], v94 offset:60992
	s_waitcnt lgkmcnt(0)
	v_pk_mul_f32 v[30:31], v[42:43], v[26:27]
	v_pk_mul_f32 v[28:29], v[40:41], v[24:25]
	v_pk_mul_f32 v[34:35], v[46:47], v[26:27]
	v_pk_mul_f32 v[32:33], v[44:45], v[24:25]
	v_pk_mul_f32 v[26:27], v[38:39], v[26:27]
	v_pk_mul_f32 v[24:25], v[36:37], v[24:25]
	ds_read_b128 v[36:39], v94 offset:61056
	s_waitcnt lgkmcnt(0)
	v_pk_mul_f32 v[42:43], v[54:55], v[38:39]
	v_pk_mul_f32 v[40:41], v[52:53], v[36:37]
	v_pk_mul_f32 v[46:47], v[58:59], v[38:39]
	v_pk_mul_f32 v[44:45], v[56:57], v[36:37]
	v_pk_mul_f32 v[38:39], v[50:51], v[38:39]
	v_pk_mul_f32 v[36:37], v[48:49], v[36:37]
	ds_read_b128 v[48:51], v94 offset:61120
	s_waitcnt lgkmcnt(0)
	s_barrier
	v_pk_mul_f32 v[2:3], v[2:3], v[50:51]
	v_pk_mul_f32 v[0:1], v[0:1], v[48:49]
	v_pk_mul_f32 v[6:7], v[6:7], v[50:51]
	v_pk_mul_f32 v[4:5], v[4:5], v[48:49]
	v_pk_mul_f32 v[10:11], v[10:11], v[50:51]
	v_pk_mul_f32 v[8:9], v[8:9], v[48:49]
	ds_read_b64_tr_b16 v[48:49], v68 offset:25600
	ds_read_b64_tr_b16 v[50:51], v68 offset:27200
	ds_read_b64_tr_b16 v[52:53], v69 offset:25600
	ds_read_b64_tr_b16 v[54:55], v69 offset:27200
	ds_read_b64_tr_b16 v[56:57], v70 offset:25600
	ds_read_b64_tr_b16 v[58:59], v70 offset:27200
	ds_read_b128 v[60:63], v166 offset:51200
	s_waitcnt lgkmcnt(0)
	v_mfma_f32_16x16x32_bf16 v[16:19], v[60:63], v[48:51], v[16:19]
	v_mfma_f32_16x16x32_bf16 v[20:23], v[60:63], v[52:55], v[20:23]
	v_mfma_f32_16x16x32_bf16 v[12:15], v[60:63], v[56:59], v[12:15]
	ds_read_b128 v[60:63], v166 offset:53504
	s_waitcnt lgkmcnt(0)
	v_mfma_f32_16x16x32_bf16 v[64:67], v[60:63], v[52:55], v[32:35]
	s_nop 2
	ds_read_b128 v[32:35], v166 offset:55808
	s_waitcnt lgkmcnt(0)
	v_mfma_f32_16x16x32_bf16 v[40:43], v[32:35], v[48:51], v[40:43]
	v_mfma_f32_16x16x32_bf16 v[44:47], v[32:35], v[52:55], v[44:47]
	v_mfma_f32_16x16x32_bf16 v[36:39], v[32:35], v[56:59], v[36:39]
	ds_read_b128 v[32:35], v166 offset:58112
	v_mfma_f32_16x16x32_bf16 v[28:31], v[60:63], v[48:51], v[28:31]
	v_mfma_f32_16x16x32_bf16 v[24:27], v[60:63], v[56:59], v[24:27]
	s_waitcnt lgkmcnt(0)
	v_mfma_f32_16x16x32_bf16 v[0:3], v[32:35], v[48:51], v[0:3]
	v_mfma_f32_16x16x32_bf16 v[4:7], v[32:35], v[52:55], v[4:7]
	v_mfma_f32_16x16x32_bf16 v[48:51], v[32:35], v[56:59], v[8:11]
	s_nop 2
	ds_read_b64_tr_b16 v[8:9], v68 offset:38400
	ds_read_b64_tr_b16 v[10:11], v68 offset:40000
	ds_read_b64_tr_b16 v[52:53], v69 offset:38400
	ds_read_b64_tr_b16 v[54:55], v69 offset:40000
	ds_read_b64_tr_b16 v[56:57], v70 offset:38400
	ds_read_b64_tr_b16 v[58:59], v70 offset:40000
	ds_read_b128 v[32:35], v166 offset:51264
	s_waitcnt lgkmcnt(0)
	v_mfma_f32_16x16x32_bf16 v[72:75], v[32:35], v[56:59], v[12:15]
	s_nop 2
	ds_read_b128 v[12:15], v166 offset:53568
	v_mfma_f32_16x16x32_bf16 v[60:63], v[32:35], v[8:11], v[16:19]
	v_mfma_f32_16x16x32_bf16 v[68:71], v[32:35], v[52:55], v[20:23]
	s_waitcnt lgkmcnt(0)
	v_mfma_f32_16x16x32_bf16 v[32:35], v[12:15], v[8:11], v[28:31]
	v_mfma_f32_16x16x32_bf16 v[28:31], v[12:15], v[52:55], v[64:67]
	v_mfma_f32_16x16x32_bf16 v[24:27], v[12:15], v[56:59], v[24:27]
	ds_read_b128 v[12:15], v166 offset:55872
	s_waitcnt lgkmcnt(0)
	v_mfma_f32_16x16x32_bf16 v[20:23], v[12:15], v[8:11], v[40:43]
	v_mfma_f32_16x16x32_bf16 v[16:19], v[12:15], v[52:55], v[44:47]
	v_mfma_f32_16x16x32_bf16 v[12:15], v[12:15], v[56:59], v[36:39]
	s_nop 2
	ds_read_b128 v[36:39], v166 offset:58176
	s_waitcnt lgkmcnt(0)
	v_mfma_f32_16x16x32_bf16 v[8:11], v[36:39], v[8:11], v[0:3]
	s_barrier
	v_mfma_f32_16x16x32_bf16 v[4:7], v[36:39], v[52:55], v[4:7]
	v_mfma_f32_16x16x32_bf16 v[0:3], v[36:39], v[56:59], v[48:51]
	ds_read_b32 v36, v94 offset:61440
	v_add_u32_e32 v38, s63, v142
	s_waitcnt lgkmcnt(0)
	v_mul_f32_e32 v37, v60, v36
	ds_write_b32 v38, v37
	v_mul_f32_e32 v37, v68, v36
	v_add_u32_e32 v38, s36, v142
	ds_write_b32 v38, v37
	v_mul_f32_e32 v36, v72, v36
	v_add_u32_e32 v37, s37, v142
	ds_write_b32 v37, v36
	ds_read_b32 v36, v94 offset:61444
	v_add_u32_e32 v38, s63, v143
	s_waitcnt lgkmcnt(0)
	v_mul_f32_e32 v37, v61, v36
	ds_write_b32 v38, v37
	v_mul_f32_e32 v37, v69, v36
	v_add_u32_e32 v38, s36, v143
	ds_write_b32 v38, v37
	v_mul_f32_e32 v36, v73, v36
	v_add_u32_e32 v37, s37, v143
	ds_write_b32 v37, v36
	ds_read_b32 v36, v94 offset:61448
	v_add_u32_e32 v38, s63, v144
	s_waitcnt lgkmcnt(0)
	v_mul_f32_e32 v37, v62, v36
	ds_write_b32 v38, v37
	v_mul_f32_e32 v37, v70, v36
	v_add_u32_e32 v38, s36, v144
	ds_write_b32 v38, v37
	v_mul_f32_e32 v36, v74, v36
	v_add_u32_e32 v37, s37, v144
	ds_write_b32 v37, v36
	ds_read_b32 v36, v94 offset:61452
	v_add_u32_e32 v38, s63, v145
	s_waitcnt lgkmcnt(0)
	v_mul_f32_e32 v37, v63, v36
	ds_write_b32 v38, v37
	v_mul_f32_e32 v37, v71, v36
	v_add_u32_e32 v38, s36, v145
	ds_write_b32 v38, v37
	v_mul_f32_e32 v36, v75, v36
	v_add_u32_e32 v37, s37, v145
	ds_write_b32 v37, v36
	ds_read_b32 v36, v94 offset:61504
	v_add_u32_e32 v37, s63, v146
	s_waitcnt lgkmcnt(0)
	v_mul_f32_e32 v32, v32, v36
	ds_write_b32 v37, v32
	v_mul_f32_e32 v28, v28, v36
	v_add_u32_e32 v32, s36, v146
	ds_write_b32 v32, v28
	v_mul_f32_e32 v24, v24, v36
	v_add_u32_e32 v28, s37, v146
	ds_write_b32 v28, v24
	ds_read_b32 v24, v94 offset:61508
	v_add_u32_e32 v32, s63, v147
	s_waitcnt lgkmcnt(0)
	v_mul_f32_e32 v28, v33, v24
	ds_write_b32 v32, v28
	v_mul_f32_e32 v28, v29, v24
	v_add_u32_e32 v29, s36, v147
	v_mul_f32_e32 v24, v25, v24
	v_add_u32_e32 v25, s37, v147
	ds_write_b32 v29, v28
	ds_write_b32 v25, v24
	ds_read_b32 v24, v94 offset:61512
	v_add_u32_e32 v28, s63, v148
	s_waitcnt lgkmcnt(0)
	v_mul_f32_e32 v25, v34, v24
	ds_write_b32 v28, v25
	v_mul_f32_e32 v25, v30, v24
	v_add_u32_e32 v28, s36, v148
	ds_write_b32 v28, v25
	v_mul_f32_e32 v24, v26, v24
	v_add_u32_e32 v25, s37, v148
	ds_write_b32 v25, v24
	ds_read_b32 v24, v94 offset:61516
	v_add_u32_e32 v26, s63, v149
	s_waitcnt lgkmcnt(0)
	v_mul_f32_e32 v25, v35, v24
	ds_write_b32 v26, v25
	v_mul_f32_e32 v25, v31, v24
	v_add_u32_e32 v26, s36, v149
	ds_write_b32 v26, v25
	v_mul_f32_e32 v24, v27, v24
	v_add_u32_e32 v25, s37, v149
	ds_write_b32 v25, v24
	ds_read_b32 v24, v94 offset:61568
	v_add_u32_e32 v25, s63, v150
	s_waitcnt lgkmcnt(0)
	v_mul_f32_e32 v20, v20, v24
	ds_write_b32 v25, v20
	v_mul_f32_e32 v16, v16, v24
	v_add_u32_e32 v20, s36, v150
	ds_write_b32 v20, v16
	v_mul_f32_e32 v12, v12, v24
	v_add_u32_e32 v16, s37, v150
	ds_write_b32 v16, v12
	ds_read_b32 v12, v94 offset:61572
	v_add_u32_e32 v20, s63, v151
	s_waitcnt lgkmcnt(0)
	v_mul_f32_e32 v16, v21, v12
	ds_write_b32 v20, v16
	v_mul_f32_e32 v16, v17, v12
	v_add_u32_e32 v17, s36, v151
	v_mul_f32_e32 v12, v13, v12
	v_add_u32_e32 v13, s37, v151
	ds_write_b32 v17, v16
	ds_write_b32 v13, v12
	ds_read_b32 v12, v94 offset:61576
	v_add_u32_e32 v16, s63, v152
	s_waitcnt lgkmcnt(0)
	v_mul_f32_e32 v13, v22, v12
	ds_write_b32 v16, v13
	v_mul_f32_e32 v13, v18, v12
	v_add_u32_e32 v16, s36, v152
	ds_write_b32 v16, v13
	v_mul_f32_e32 v12, v14, v12
	v_add_u32_e32 v13, s37, v152
	ds_write_b32 v13, v12
	ds_read_b32 v12, v94 offset:61580
	v_add_u32_e32 v14, s63, v153
	s_waitcnt lgkmcnt(0)
	v_mul_f32_e32 v13, v23, v12
	ds_write_b32 v14, v13
	v_mul_f32_e32 v13, v19, v12
	v_add_u32_e32 v14, s36, v153
	ds_write_b32 v14, v13
	v_mul_f32_e32 v12, v15, v12
	v_add_u32_e32 v13, s37, v153
	ds_write_b32 v13, v12
	ds_read_b32 v12, v94 offset:61632
	v_add_u32_e32 v13, s63, v154
	s_waitcnt lgkmcnt(0)
	v_mul_f32_e32 v8, v8, v12
	ds_write_b32 v13, v8
	v_mul_f32_e32 v4, v4, v12
	v_add_u32_e32 v8, s36, v154
	ds_write_b32 v8, v4
	v_mul_f32_e32 v0, v0, v12
	v_add_u32_e32 v4, s37, v154
	ds_write_b32 v4, v0
	ds_read_b32 v0, v94 offset:61636
	v_add_u32_e32 v8, s63, v155
	s_waitcnt lgkmcnt(0)
	v_mul_f32_e32 v4, v9, v0
	ds_write_b32 v8, v4
	v_mul_f32_e32 v4, v5, v0
	v_add_u32_e32 v5, s36, v155
	v_mul_f32_e32 v0, v1, v0
	v_add_u32_e32 v1, s37, v155
	ds_write_b32 v5, v4
	ds_write_b32 v1, v0
	ds_read_b32 v0, v94 offset:61640
	v_add_u32_e32 v4, s63, v156
	s_waitcnt lgkmcnt(0)
	v_mul_f32_e32 v1, v10, v0
	ds_write_b32 v4, v1
	v_mul_f32_e32 v1, v6, v0
	v_add_u32_e32 v4, s36, v156
	ds_write_b32 v4, v1
	v_mul_f32_e32 v0, v2, v0
	v_add_u32_e32 v1, s37, v156
	ds_write_b32 v1, v0
	ds_read_b32 v0, v94 offset:61644
	v_add_u32_e32 v2, s63, v157
	s_waitcnt lgkmcnt(0)
	v_mul_f32_e32 v1, v11, v0
	ds_write_b32 v2, v1
	v_mul_f32_e32 v1, v7, v0
	v_add_u32_e32 v2, s36, v157
	ds_write_b32 v2, v1
	v_mul_f32_e32 v0, v3, v0
	v_add_u32_e32 v1, s37, v157
	ds_write_b32 v1, v0
	ds_write_b32 v101, v246 offset:62464
	v_or_b32_e32 v202, v125, v108
	v_mov_b64_e32 v[200:201], s[60:61]
	v_mad_u64_u32 v[200:201], vcc, v202, s50, v[200:201]
	v_mov_b32_e32 v202, v201
	v_mad_u64_u32 v[202:203], vcc, v127, s50, v[202:203]
	v_mov_b32_e32 v201, v202
	v_lshl_add_u64 v[200:201], v[200:201], 0, v[90:91]
	v_mov_b32_e32 v202, v124
	v_mov_b32_e32 v203, v91
	v_lshl_add_u64 v[200:201], v[200:201], 0, v[202:203]
	v_lshl_add_u64 v[200:201], v[200:201], 0, s[34:35]
	global_load_dwordx4 v[206:209], v[200:201], off
	global_load_dwordx4 v[210:213], v[200:201], off offset:16
	global_load_dwordx4 v[214:217], v[200:201], off offset:32
	global_load_dwordx4 v[218:221], v[200:201], off offset:48
	global_load_dwordx4 v[222:225], v[200:201], off offset:64
	global_load_dwordx4 v[226:229], v[200:201], off offset:80
	s_waitcnt lgkmcnt(0)
	s_barrier
	ds_read_b128 v[8:11], v167
	ds_read_b128 v[18:21], v167 offset:16
	ds_read_b128 v[22:25], v167 offset:32
	ds_read_b128 v[4:7], v167 offset:48
	s_waitcnt lgkmcnt(3)
	v_mul_f32_e32 v0, v9, v9
	v_pk_fma_f32 v[0:1], v[8:9], v[8:9], v[0:1] op_sel_hi:[1,1,0]
	s_waitcnt lgkmcnt(1)
	v_mul_f32_e32 v2, v22, v22
	v_mov_b32_e32 v1, v2
	v_mul_f32_e32 v2, v11, v11
	v_mul_f32_e32 v12, v23, v23
	v_pk_fma_f32 v[2:3], v[10:11], v[10:11], v[2:3] op_sel_hi:[1,1,0]
	v_mul_f32_e32 v13, v24, v24
	v_mov_b32_e32 v3, v12
	v_pk_add_f32 v[0:1], v[0:1], v[2:3]
	v_mul_f32_e32 v2, v19, v19
	v_pk_fma_f32 v[2:3], v[18:19], v[18:19], v[2:3] op_sel_hi:[1,1,0]
	v_mul_f32_e32 v12, v21, v21
	v_mul_f32_e32 v14, v25, v25
	v_mov_b32_e32 v3, v13
	v_pk_fma_f32 v[12:13], v[20:21], v[20:21], v[12:13] op_sel_hi:[1,1,0]
	s_nop 0
	v_mov_b32_e32 v13, v14
	v_pk_add_f32 v[2:3], v[2:3], v[12:13]
	s_nop 0
	v_pk_add_f32 v[16:17], v[0:1], v[2:3]
	s_waitcnt lgkmcnt(0)
	v_pk_mul_f32 v[0:1], v[6:7], v[6:7]
	v_pk_mul_f32 v[2:3], v[4:5], v[4:5]
	s_nop 0
	v_pk_mov_b32 v[12:13], v[2:3], v[0:1] op_sel:[1,0]
	v_mov_b32_e32 v3, v1
	v_pk_add_f32 v[26:27], v[12:13], v[2:3]
	ds_read_b128 v[0:3], v167 offset:64
	ds_read_b128 v[12:15], v167 offset:80
	s_waitcnt lgkmcnt(0)
	v_mul_f32_e32 v28, v12, v12
	v_mul_f32_e32 v29, v13, v13
	v_mul_f32_e32 v30, v14, v14
	v_mul_f32_e32 v31, v15, v15
	v_pk_add_f32 v[12:13], v[16:17], v[16:17] op_sel:[0,1] op_sel_hi:[1,0]
	v_pk_add_f32 v[14:15], v[26:27], v[26:27] op_sel:[0,1] op_sel_hi:[1,0]
	v_mov_b32_e32 v13, v28
	v_mov_b32_e32 v15, v29
	v_pk_add_f32 v[12:13], v[12:13], v[14:15]
	v_mul_f32_e32 v14, v1, v1
	v_pk_fma_f32 v[0:1], v[0:1], v[0:1], v[14:15] op_sel_hi:[1,1,0]
	v_mul_f32_e32 v14, v3, v3
	v_pk_fma_f32 v[2:3], v[2:3], v[2:3], v[14:15] op_sel_hi:[1,1,0]
	v_mov_b32_e32 v1, v30
	v_mov_b32_e32 v3, v31
	v_pk_add_f32 v[0:1], v[0:1], v[2:3]
	s_nop 0
	v_pk_add_f32 v[16:17], v[12:13], v[0:1]
	ds_read_b128 v[0:3], v167 offset:96
	s_waitcnt lgkmcnt(0)
	v_pk_mul_f32 v[2:3], v[2:3], v[2:3]
	v_pk_mul_f32 v[0:1], v[0:1], v[0:1]
	s_nop 0
	v_pk_mov_b32 v[12:13], v[0:1], v[2:3] op_sel:[1,0]
	v_mov_b32_e32 v1, v3
	v_pk_add_f32 v[26:27], v[12:13], v[0:1]
	ds_read_b128 v[0:3], v167 offset:112
	ds_read_b128 v[12:15], v167 offset:128
	s_waitcnt lgkmcnt(0)
	v_mul_f32_e32 v28, v12, v12
	v_mul_f32_e32 v29, v13, v13
	v_mul_f32_e32 v30, v14, v14
	v_mul_f32_e32 v31, v15, v15
	v_pk_add_f32 v[12:13], v[16:17], v[16:17] op_sel:[0,1] op_sel_hi:[1,0]
	v_pk_add_f32 v[14:15], v[26:27], v[26:27] op_sel:[0,1] op_sel_hi:[1,0]
	v_mov_b32_e32 v13, v28
	v_mov_b32_e32 v15, v29
	v_pk_add_f32 v[12:13], v[12:13], v[14:15]
	v_mul_f32_e32 v14, v1, v1
	v_pk_fma_f32 v[0:1], v[0:1], v[0:1], v[14:15] op_sel_hi:[1,1,0]
	v_mul_f32_e32 v14, v3, v3
	v_pk_fma_f32 v[2:3], v[2:3], v[2:3], v[14:15] op_sel_hi:[1,1,0]
	v_mov_b32_e32 v1, v30
	v_mov_b32_e32 v3, v31
	v_pk_add_f32 v[0:1], v[0:1], v[2:3]
	s_nop 0
	v_pk_add_f32 v[16:17], v[12:13], v[0:1]
	ds_read_b128 v[0:3], v167 offset:144
	s_waitcnt lgkmcnt(0)
	v_pk_mul_f32 v[2:3], v[2:3], v[2:3]
	v_pk_mul_f32 v[0:1], v[0:1], v[0:1]
	s_nop 0
	v_pk_mov_b32 v[12:13], v[0:1], v[2:3] op_sel:[1,0]
	v_mov_b32_e32 v1, v3
	v_pk_add_f32 v[26:27], v[12:13], v[0:1]
	ds_read_b128 v[0:3], v167 offset:160
	ds_read_b128 v[12:15], v167 offset:176
	s_waitcnt lgkmcnt(0)
	v_mul_f32_e32 v28, v12, v12
	v_mul_f32_e32 v29, v13, v13
	v_mul_f32_e32 v30, v14, v14
	v_mul_f32_e32 v31, v15, v15
	v_pk_add_f32 v[12:13], v[16:17], v[16:17] op_sel:[0,1] op_sel_hi:[1,0]
	v_pk_add_f32 v[14:15], v[26:27], v[26:27] op_sel:[0,1] op_sel_hi:[1,0]
	v_mov_b32_e32 v13, v28
	v_mov_b32_e32 v15, v29
	v_pk_add_f32 v[12:13], v[12:13], v[14:15]
	v_mul_f32_e32 v14, v1, v1
	v_pk_fma_f32 v[0:1], v[0:1], v[0:1], v[14:15] op_sel_hi:[1,1,0]
	v_mul_f32_e32 v14, v3, v3
	v_pk_fma_f32 v[2:3], v[2:3], v[2:3], v[14:15] op_sel_hi:[1,1,0]
	v_mov_b32_e32 v1, v30
	v_mov_b32_e32 v3, v31
	v_pk_add_f32 v[0:1], v[0:1], v[2:3]
	v_pk_add_f32 v[0:1], v[12:13], v[0:1]
	v_add_f32_e32 v0, v0, v1
	ds_bpermute_b32 v1, v139, v0
	s_waitcnt lgkmcnt(0)
	v_add_f32_e32 v0, v0, v1
	ds_bpermute_b32 v1, v140, v0
	s_waitcnt lgkmcnt(0)
	v_add_f32_e32 v0, v0, v1
	v_fmamk_f32 v0, v0, 0x3baaaaab, v168
	v_cmp_gt_f32_e32 vcc, s55, v0
	v_mul_f32_e32 v1, 0x4b800000, v0
	s_nop 0
	v_cndmask_b32_e32 v0, v0, v1, vcc
	v_rsq_f32_e32 v0, v0
	s_nop 0
	v_mul_f32_e32 v1, 0x45800000, v0
	v_cndmask_b32_e32 v14, v0, v1, vcc
	s_waitcnt vmcnt(0)
	ds_read_b128 v[0:3], v167 offset:0
	ds_read_b128 v[4:7], v167 offset:16
	ds_read_b128 v[16:19], v138 offset:62464
	ds_read_b128 v[20:23], v138 offset:62480
	ds_read_b128 v[32:35], v167 offset:32
	ds_read_b128 v[36:39], v167 offset:48
	ds_read_b128 v[40:43], v138 offset:62496
	ds_read_b128 v[44:47], v138 offset:62512
	v_lshlrev_b32_e32 v24, 16, v206
	v_and_b32_e32 v25, 0xffff0000, v206
	v_lshlrev_b32_e32 v26, 16, v207
	v_and_b32_e32 v27, 0xffff0000, v207
	v_lshlrev_b32_e32 v28, 16, v208
	v_and_b32_e32 v29, 0xffff0000, v208
	v_lshlrev_b32_e32 v30, 16, v209
	v_and_b32_e32 v31, 0xffff0000, v209
	v_mul_f32_e32 v24, 0xbfb8aa3b, v24
	v_mul_f32_e32 v25, 0xbfb8aa3b, v25
	v_mul_f32_e32 v26, 0xbfb8aa3b, v26
	v_mul_f32_e32 v27, 0xbfb8aa3b, v27
	v_mul_f32_e32 v28, 0xbfb8aa3b, v28
	v_mul_f32_e32 v29, 0xbfb8aa3b, v29
	v_mul_f32_e32 v30, 0xbfb8aa3b, v30
	v_mul_f32_e32 v31, 0xbfb8aa3b, v31
	v_exp_f32_e32 v24, v24
	v_exp_f32_e32 v25, v25
	v_exp_f32_e32 v26, v26
	v_exp_f32_e32 v27, v27
	v_exp_f32_e32 v28, v28
	v_exp_f32_e32 v29, v29
	v_exp_f32_e32 v30, v30
	v_exp_f32_e32 v31, v31
	v_add_f32_e32 v24, 1.0, v24
	v_add_f32_e32 v25, 1.0, v25
	v_add_f32_e32 v26, 1.0, v26
	v_add_f32_e32 v27, 1.0, v27
	v_add_f32_e32 v28, 1.0, v28
	v_add_f32_e32 v29, 1.0, v29
	v_add_f32_e32 v30, 1.0, v30
	v_add_f32_e32 v31, 1.0, v31
	v_rcp_f32_e32 v24, v24
	v_rcp_f32_e32 v25, v25
	v_rcp_f32_e32 v26, v26
	v_rcp_f32_e32 v27, v27
	v_rcp_f32_e32 v28, v28
	v_rcp_f32_e32 v29, v29
	v_rcp_f32_e32 v30, v30
	v_rcp_f32_e32 v31, v31
	s_waitcnt lgkmcnt(4)
	v_pk_mul_f32 v[0:1], v[0:1], v[14:15] op_sel_hi:[1,0]
	v_pk_mul_f32 v[2:3], v[2:3], v[14:15] op_sel_hi:[1,0]
	v_pk_mul_f32 v[4:5], v[4:5], v[14:15] op_sel_hi:[1,0]
	v_pk_mul_f32 v[6:7], v[6:7], v[14:15] op_sel_hi:[1,0]
	v_pk_mul_f32 v[0:1], v[16:17], v[0:1]
	v_pk_mul_f32 v[2:3], v[18:19], v[2:3]
	v_pk_mul_f32 v[4:5], v[20:21], v[4:5]
	v_pk_mul_f32 v[6:7], v[22:23], v[6:7]
	v_pk_mul_f32 v[0:1], v[24:25], v[0:1]
	v_pk_mul_f32 v[2:3], v[26:27], v[2:3]
	v_pk_mul_f32 v[4:5], v[28:29], v[4:5]
	v_pk_mul_f32 v[6:7], v[30:31], v[6:7]
	v_cvt_pk_bf16_f32 v8, v0, v1
	v_cvt_pk_bf16_f32 v9, v2, v3
	v_cvt_pk_bf16_f32 v10, v4, v5
	v_cvt_pk_bf16_f32 v11, v6, v7
	global_store_dwordx4 v[200:201], v[8:11], off nt
	ds_read_b128 v[0:3], v167 offset:64
	ds_read_b128 v[4:7], v167 offset:80
	ds_read_b128 v[16:19], v138 offset:62528
	ds_read_b128 v[20:23], v138 offset:62544
	v_lshlrev_b32_e32 v24, 16, v210
	v_and_b32_e32 v25, 0xffff0000, v210
	v_lshlrev_b32_e32 v26, 16, v211
	v_and_b32_e32 v27, 0xffff0000, v211
	v_lshlrev_b32_e32 v28, 16, v212
	v_and_b32_e32 v29, 0xffff0000, v212
	v_lshlrev_b32_e32 v30, 16, v213
	v_and_b32_e32 v31, 0xffff0000, v213
	v_mul_f32_e32 v24, 0xbfb8aa3b, v24
	v_mul_f32_e32 v25, 0xbfb8aa3b, v25
	v_mul_f32_e32 v26, 0xbfb8aa3b, v26
	v_mul_f32_e32 v27, 0xbfb8aa3b, v27
	v_mul_f32_e32 v28, 0xbfb8aa3b, v28
	v_mul_f32_e32 v29, 0xbfb8aa3b, v29
	v_mul_f32_e32 v30, 0xbfb8aa3b, v30
	v_mul_f32_e32 v31, 0xbfb8aa3b, v31
	v_exp_f32_e32 v24, v24
	v_exp_f32_e32 v25, v25
	v_exp_f32_e32 v26, v26
	v_exp_f32_e32 v27, v27
	v_exp_f32_e32 v28, v28
	v_exp_f32_e32 v29, v29
	v_exp_f32_e32 v30, v30
	v_exp_f32_e32 v31, v31
	v_add_f32_e32 v24, 1.0, v24
	v_add_f32_e32 v25, 1.0, v25
	v_add_f32_e32 v26, 1.0, v26
	v_add_f32_e32 v27, 1.0, v27
	v_add_f32_e32 v28, 1.0, v28
	v_add_f32_e32 v29, 1.0, v29
	v_add_f32_e32 v30, 1.0, v30
	v_add_f32_e32 v31, 1.0, v31
	v_rcp_f32_e32 v24, v24
	v_rcp_f32_e32 v25, v25
	v_rcp_f32_e32 v26, v26
	v_rcp_f32_e32 v27, v27
	v_rcp_f32_e32 v28, v28
	v_rcp_f32_e32 v29, v29
	v_rcp_f32_e32 v30, v30
	v_rcp_f32_e32 v31, v31
	s_waitcnt lgkmcnt(4)
	v_pk_mul_f32 v[32:33], v[32:33], v[14:15] op_sel_hi:[1,0]
	v_pk_mul_f32 v[34:35], v[34:35], v[14:15] op_sel_hi:[1,0]
	v_pk_mul_f32 v[36:37], v[36:37], v[14:15] op_sel_hi:[1,0]
	v_pk_mul_f32 v[38:39], v[38:39], v[14:15] op_sel_hi:[1,0]
	v_pk_mul_f32 v[32:33], v[40:41], v[32:33]
	v_pk_mul_f32 v[34:35], v[42:43], v[34:35]
	v_pk_mul_f32 v[36:37], v[44:45], v[36:37]
	v_pk_mul_f32 v[38:39], v[46:47], v[38:39]
	v_pk_mul_f32 v[32:33], v[24:25], v[32:33]
	v_pk_mul_f32 v[34:35], v[26:27], v[34:35]
	v_pk_mul_f32 v[36:37], v[28:29], v[36:37]
	v_pk_mul_f32 v[38:39], v[30:31], v[38:39]
	v_cvt_pk_bf16_f32 v8, v32, v33
	v_cvt_pk_bf16_f32 v9, v34, v35
	v_cvt_pk_bf16_f32 v10, v36, v37
	v_cvt_pk_bf16_f32 v11, v38, v39
	global_store_dwordx4 v[200:201], v[8:11], off offset:16 nt
	ds_read_b128 v[32:35], v167 offset:96
	ds_read_b128 v[36:39], v167 offset:112
	ds_read_b128 v[40:43], v138 offset:62560
	ds_read_b128 v[44:47], v138 offset:62576
	v_lshlrev_b32_e32 v24, 16, v214
	v_and_b32_e32 v25, 0xffff0000, v214
	v_lshlrev_b32_e32 v26, 16, v215
	v_and_b32_e32 v27, 0xffff0000, v215
	v_lshlrev_b32_e32 v28, 16, v216
	v_and_b32_e32 v29, 0xffff0000, v216
	v_lshlrev_b32_e32 v30, 16, v217
	v_and_b32_e32 v31, 0xffff0000, v217
	v_mul_f32_e32 v24, 0xbfb8aa3b, v24
	v_mul_f32_e32 v25, 0xbfb8aa3b, v25
	v_mul_f32_e32 v26, 0xbfb8aa3b, v26
	v_mul_f32_e32 v27, 0xbfb8aa3b, v27
	v_mul_f32_e32 v28, 0xbfb8aa3b, v28
	v_mul_f32_e32 v29, 0xbfb8aa3b, v29
	v_mul_f32_e32 v30, 0xbfb8aa3b, v30
	v_mul_f32_e32 v31, 0xbfb8aa3b, v31
	v_exp_f32_e32 v24, v24
	v_exp_f32_e32 v25, v25
	v_exp_f32_e32 v26, v26
	v_exp_f32_e32 v27, v27
	v_exp_f32_e32 v28, v28
	v_exp_f32_e32 v29, v29
	v_exp_f32_e32 v30, v30
	v_exp_f32_e32 v31, v31
	v_add_f32_e32 v24, 1.0, v24
	v_add_f32_e32 v25, 1.0, v25
	v_add_f32_e32 v26, 1.0, v26
	v_add_f32_e32 v27, 1.0, v27
	v_add_f32_e32 v28, 1.0, v28
	v_add_f32_e32 v29, 1.0, v29
	v_add_f32_e32 v30, 1.0, v30
	v_add_f32_e32 v31, 1.0, v31
	v_rcp_f32_e32 v24, v24
	v_rcp_f32_e32 v25, v25
	v_rcp_f32_e32 v26, v26
	v_rcp_f32_e32 v27, v27
	v_rcp_f32_e32 v28, v28
	v_rcp_f32_e32 v29, v29
	v_rcp_f32_e32 v30, v30
	v_rcp_f32_e32 v31, v31
	s_waitcnt lgkmcnt(4)
	v_pk_mul_f32 v[0:1], v[0:1], v[14:15] op_sel_hi:[1,0]
	v_pk_mul_f32 v[2:3], v[2:3], v[14:15] op_sel_hi:[1,0]
	v_pk_mul_f32 v[4:5], v[4:5], v[14:15] op_sel_hi:[1,0]
	v_pk_mul_f32 v[6:7], v[6:7], v[14:15] op_sel_hi:[1,0]
	v_pk_mul_f32 v[0:1], v[16:17], v[0:1]
	v_pk_mul_f32 v[2:3], v[18:19], v[2:3]
	v_pk_mul_f32 v[4:5], v[20:21], v[4:5]
	v_pk_mul_f32 v[6:7], v[22:23], v[6:7]
	v_pk_mul_f32 v[0:1], v[24:25], v[0:1]
	v_pk_mul_f32 v[2:3], v[26:27], v[2:3]
	v_pk_mul_f32 v[4:5], v[28:29], v[4:5]
	v_pk_mul_f32 v[6:7], v[30:31], v[6:7]
	v_cvt_pk_bf16_f32 v8, v0, v1
	v_cvt_pk_bf16_f32 v9, v2, v3
	v_cvt_pk_bf16_f32 v10, v4, v5
	v_cvt_pk_bf16_f32 v11, v6, v7
	global_store_dwordx4 v[200:201], v[8:11], off offset:32 nt
	ds_read_b128 v[0:3], v167 offset:128
	ds_read_b128 v[4:7], v167 offset:144
	ds_read_b128 v[16:19], v138 offset:62592
	ds_read_b128 v[20:23], v138 offset:62608
	v_lshlrev_b32_e32 v24, 16, v218
	v_and_b32_e32 v25, 0xffff0000, v218
	v_lshlrev_b32_e32 v26, 16, v219
	v_and_b32_e32 v27, 0xffff0000, v219
	v_lshlrev_b32_e32 v28, 16, v220
	v_and_b32_e32 v29, 0xffff0000, v220
	v_lshlrev_b32_e32 v30, 16, v221
	v_and_b32_e32 v31, 0xffff0000, v221
	v_mul_f32_e32 v24, 0xbfb8aa3b, v24
	v_mul_f32_e32 v25, 0xbfb8aa3b, v25
	v_mul_f32_e32 v26, 0xbfb8aa3b, v26
	v_mul_f32_e32 v27, 0xbfb8aa3b, v27
	v_mul_f32_e32 v28, 0xbfb8aa3b, v28
	v_mul_f32_e32 v29, 0xbfb8aa3b, v29
	v_mul_f32_e32 v30, 0xbfb8aa3b, v30
	v_mul_f32_e32 v31, 0xbfb8aa3b, v31
	v_exp_f32_e32 v24, v24
	v_exp_f32_e32 v25, v25
	v_exp_f32_e32 v26, v26
	v_exp_f32_e32 v27, v27
	v_exp_f32_e32 v28, v28
	v_exp_f32_e32 v29, v29
	v_exp_f32_e32 v30, v30
	v_exp_f32_e32 v31, v31
	v_add_f32_e32 v24, 1.0, v24
	v_add_f32_e32 v25, 1.0, v25
	v_add_f32_e32 v26, 1.0, v26
	v_add_f32_e32 v27, 1.0, v27
	v_add_f32_e32 v28, 1.0, v28
	v_add_f32_e32 v29, 1.0, v29
	v_add_f32_e32 v30, 1.0, v30
	v_add_f32_e32 v31, 1.0, v31
	v_rcp_f32_e32 v24, v24
	v_rcp_f32_e32 v25, v25
	v_rcp_f32_e32 v26, v26
	v_rcp_f32_e32 v27, v27
	v_rcp_f32_e32 v28, v28
	v_rcp_f32_e32 v29, v29
	v_rcp_f32_e32 v30, v30
	v_rcp_f32_e32 v31, v31
	s_waitcnt lgkmcnt(4)
	v_pk_mul_f32 v[32:33], v[32:33], v[14:15] op_sel_hi:[1,0]
	v_pk_mul_f32 v[34:35], v[34:35], v[14:15] op_sel_hi:[1,0]
	v_pk_mul_f32 v[36:37], v[36:37], v[14:15] op_sel_hi:[1,0]
	v_pk_mul_f32 v[38:39], v[38:39], v[14:15] op_sel_hi:[1,0]
	v_pk_mul_f32 v[32:33], v[40:41], v[32:33]
	v_pk_mul_f32 v[34:35], v[42:43], v[34:35]
	v_pk_mul_f32 v[36:37], v[44:45], v[36:37]
	v_pk_mul_f32 v[38:39], v[46:47], v[38:39]
	v_pk_mul_f32 v[32:33], v[24:25], v[32:33]
	v_pk_mul_f32 v[34:35], v[26:27], v[34:35]
	v_pk_mul_f32 v[36:37], v[28:29], v[36:37]
	v_pk_mul_f32 v[38:39], v[30:31], v[38:39]
	v_cvt_pk_bf16_f32 v8, v32, v33
	v_cvt_pk_bf16_f32 v9, v34, v35
	v_cvt_pk_bf16_f32 v10, v36, v37
	v_cvt_pk_bf16_f32 v11, v38, v39
	global_store_dwordx4 v[200:201], v[8:11], off offset:48 nt
	ds_read_b128 v[32:35], v167 offset:160
	ds_read_b128 v[36:39], v167 offset:176
	ds_read_b128 v[40:43], v138 offset:62624
	ds_read_b128 v[44:47], v138 offset:62640
	v_lshlrev_b32_e32 v24, 16, v222
	v_and_b32_e32 v25, 0xffff0000, v222
	v_lshlrev_b32_e32 v26, 16, v223
	v_and_b32_e32 v27, 0xffff0000, v223
	v_lshlrev_b32_e32 v28, 16, v224
	v_and_b32_e32 v29, 0xffff0000, v224
	v_lshlrev_b32_e32 v30, 16, v225
	v_and_b32_e32 v31, 0xffff0000, v225
	v_mul_f32_e32 v24, 0xbfb8aa3b, v24
	v_mul_f32_e32 v25, 0xbfb8aa3b, v25
	v_mul_f32_e32 v26, 0xbfb8aa3b, v26
	v_mul_f32_e32 v27, 0xbfb8aa3b, v27
	v_mul_f32_e32 v28, 0xbfb8aa3b, v28
	v_mul_f32_e32 v29, 0xbfb8aa3b, v29
	v_mul_f32_e32 v30, 0xbfb8aa3b, v30
	v_mul_f32_e32 v31, 0xbfb8aa3b, v31
	v_exp_f32_e32 v24, v24
	v_exp_f32_e32 v25, v25
	v_exp_f32_e32 v26, v26
	v_exp_f32_e32 v27, v27
	v_exp_f32_e32 v28, v28
	v_exp_f32_e32 v29, v29
	v_exp_f32_e32 v30, v30
	v_exp_f32_e32 v31, v31
	v_add_f32_e32 v24, 1.0, v24
	v_add_f32_e32 v25, 1.0, v25
	v_add_f32_e32 v26, 1.0, v26
	v_add_f32_e32 v27, 1.0, v27
	v_add_f32_e32 v28, 1.0, v28
	v_add_f32_e32 v29, 1.0, v29
	v_add_f32_e32 v30, 1.0, v30
	v_add_f32_e32 v31, 1.0, v31
	v_rcp_f32_e32 v24, v24
	v_rcp_f32_e32 v25, v25
	v_rcp_f32_e32 v26, v26
	v_rcp_f32_e32 v27, v27
	v_rcp_f32_e32 v28, v28
	v_rcp_f32_e32 v29, v29
	v_rcp_f32_e32 v30, v30
	v_rcp_f32_e32 v31, v31
	s_waitcnt lgkmcnt(4)
	v_pk_mul_f32 v[0:1], v[0:1], v[14:15] op_sel_hi:[1,0]
	v_pk_mul_f32 v[2:3], v[2:3], v[14:15] op_sel_hi:[1,0]
	v_pk_mul_f32 v[4:5], v[4:5], v[14:15] op_sel_hi:[1,0]
	v_pk_mul_f32 v[6:7], v[6:7], v[14:15] op_sel_hi:[1,0]
	v_pk_mul_f32 v[0:1], v[16:17], v[0:1]
	v_pk_mul_f32 v[2:3], v[18:19], v[2:3]
	v_pk_mul_f32 v[4:5], v[20:21], v[4:5]
	v_pk_mul_f32 v[6:7], v[22:23], v[6:7]
	v_pk_mul_f32 v[0:1], v[24:25], v[0:1]
	v_pk_mul_f32 v[2:3], v[26:27], v[2:3]
	v_pk_mul_f32 v[4:5], v[28:29], v[4:5]
	v_pk_mul_f32 v[6:7], v[30:31], v[6:7]
	v_cvt_pk_bf16_f32 v8, v0, v1
	v_cvt_pk_bf16_f32 v9, v2, v3
	v_cvt_pk_bf16_f32 v10, v4, v5
	v_cvt_pk_bf16_f32 v11, v6, v7
	global_store_dwordx4 v[200:201], v[8:11], off offset:64 nt
	v_lshlrev_b32_e32 v24, 16, v226
	v_and_b32_e32 v25, 0xffff0000, v226
	v_lshlrev_b32_e32 v26, 16, v227
	v_and_b32_e32 v27, 0xffff0000, v227
	v_lshlrev_b32_e32 v28, 16, v228
	v_and_b32_e32 v29, 0xffff0000, v228
	v_lshlrev_b32_e32 v30, 16, v229
	v_and_b32_e32 v31, 0xffff0000, v229
	v_mul_f32_e32 v24, 0xbfb8aa3b, v24
	v_mul_f32_e32 v25, 0xbfb8aa3b, v25
	v_mul_f32_e32 v26, 0xbfb8aa3b, v26
	v_mul_f32_e32 v27, 0xbfb8aa3b, v27
	v_mul_f32_e32 v28, 0xbfb8aa3b, v28
	v_mul_f32_e32 v29, 0xbfb8aa3b, v29
	v_mul_f32_e32 v30, 0xbfb8aa3b, v30
	v_mul_f32_e32 v31, 0xbfb8aa3b, v31
	v_exp_f32_e32 v24, v24
	v_exp_f32_e32 v25, v25
	v_exp_f32_e32 v26, v26
	v_exp_f32_e32 v27, v27
	v_exp_f32_e32 v28, v28
	v_exp_f32_e32 v29, v29
	v_exp_f32_e32 v30, v30
	v_exp_f32_e32 v31, v31
	v_add_f32_e32 v24, 1.0, v24
	v_add_f32_e32 v25, 1.0, v25
	v_add_f32_e32 v26, 1.0, v26
	v_add_f32_e32 v27, 1.0, v27
	v_add_f32_e32 v28, 1.0, v28
	v_add_f32_e32 v29, 1.0, v29
	v_add_f32_e32 v30, 1.0, v30
	v_add_f32_e32 v31, 1.0, v31
	v_rcp_f32_e32 v24, v24
	v_rcp_f32_e32 v25, v25
	v_rcp_f32_e32 v26, v26
	v_rcp_f32_e32 v27, v27
	v_rcp_f32_e32 v28, v28
	v_rcp_f32_e32 v29, v29
	v_rcp_f32_e32 v30, v30
	v_rcp_f32_e32 v31, v31
	s_waitcnt lgkmcnt(0)
	v_pk_mul_f32 v[32:33], v[32:33], v[14:15] op_sel_hi:[1,0]
	v_pk_mul_f32 v[34:35], v[34:35], v[14:15] op_sel_hi:[1,0]
	v_pk_mul_f32 v[36:37], v[36:37], v[14:15] op_sel_hi:[1,0]
	v_pk_mul_f32 v[38:39], v[38:39], v[14:15] op_sel_hi:[1,0]
	v_pk_mul_f32 v[32:33], v[40:41], v[32:33]
	v_pk_mul_f32 v[34:35], v[42:43], v[34:35]
	v_pk_mul_f32 v[36:37], v[44:45], v[36:37]
	v_pk_mul_f32 v[38:39], v[46:47], v[38:39]
	v_pk_mul_f32 v[32:33], v[24:25], v[32:33]
	v_pk_mul_f32 v[34:35], v[26:27], v[34:35]
	v_pk_mul_f32 v[36:37], v[28:29], v[36:37]
	v_pk_mul_f32 v[38:39], v[30:31], v[38:39]
	v_cvt_pk_bf16_f32 v8, v32, v33
	v_cvt_pk_bf16_f32 v9, v34, v35
	v_cvt_pk_bf16_f32 v10, v36, v37
	v_cvt_pk_bf16_f32 v11, v38, v39
	global_store_dwordx4 v[200:201], v[8:11], off offset:80 nt
	s_cbranch_scc0 .LBB0_561

.LBB0_1038:
	v_mov_b32_e32 v0, v135
	s_nop 1
	v_permlane16_swap_b32_e32 v135, v0
	v_add_f32_e32 v0, v135, v0
	v_mov_b32_e32 v1, v0
	s_nop 1
	v_permlane32_swap_b32_e32 v0, v1
	s_lshl_b64 s[0:1], s[22:23], 11
	v_add_f32_e32 v2, v0, v1
	s_add_u32 s0, s70, s0
	v_div_scale_f32 v3, s[2:3], v2, v2, 1.0
	s_addc_u32 s1, s71, s1
	v_rcp_f32_e32 v6, v3
	s_add_u32 s0, s0, s24
	s_addc_u32 s1, s1, s25
	v_mov_b32_e32 v133, v153
	v_lshl_add_u64 v[0:1], s[0:1], 0, v[132:133]
	v_mov_b32_e32 v135, v153
	v_lshl_add_u64 v[4:5], v[0:1], 0, v[134:135]
	v_fma_f32 v0, -v3, v6, 1.0
	v_fmac_f32_e32 v6, v0, v6
	v_div_scale_f32 v0, vcc, 1.0, v2, 1.0
	v_mul_f32_e32 v1, v0, v6
	v_fma_f32 v7, -v3, v1, v0
	v_fmac_f32_e32 v1, v7, v6
	v_fma_f32 v0, -v3, v1, v0
	v_div_fmas_f32 v0, v0, v6, v1
	v_div_fixup_f32 v6, v0, v2, 1.0
	v_pk_mul_f32 v[0:1], v[56:57], v[6:7] op_sel_hi:[1,0]
	v_pk_mul_f32 v[2:3], v[58:59], v[6:7] op_sel_hi:[1,0]
	v_cvt_pk_bf16_f32 v0, v0, v1
	v_cvt_pk_bf16_f32 v1, v2, v3
	v_pk_mul_f32 v[2:3], v[60:61], v[6:7] op_sel_hi:[1,0]
	s_waitcnt vmcnt(1)
	v_pk_mul_f32 v[10:11], v[62:63], v[6:7] op_sel_hi:[1,0]
	v_mov_b32_e32 v137, v153
	v_cvt_pk_bf16_f32 v2, v2, v3
	v_cvt_pk_bf16_f32 v3, v10, v11
	v_lshl_add_u64 v[8:9], v[4:5], 0, v[136:137]
	v_permlane16_swap_b32_e32 v0, v2
	v_permlane16_swap_b32_e32 v1, v3
	global_store_dwordx4 v[8:9], v[0:3], off nt
	v_mov_b32_e32 v139, v153
	v_lshl_add_u64 v[4:5], v[4:5], 0, v[138:139]
	v_pk_mul_f32 v[0:1], v[52:53], v[6:7] op_sel_hi:[1,0]
	v_pk_mul_f32 v[2:3], v[54:55], v[6:7] op_sel_hi:[1,0]
	v_cvt_pk_bf16_f32 v0, v0, v1
	v_cvt_pk_bf16_f32 v1, v2, v3
	v_pk_mul_f32 v[2:3], v[44:45], v[6:7] op_sel_hi:[1,0]
	v_pk_mul_f32 v[6:7], v[46:47], v[6:7] op_sel_hi:[1,0]
	v_cvt_pk_bf16_f32 v2, v2, v3
	v_cvt_pk_bf16_f32 v3, v6, v7
	v_mov_b32_e32 v6, v131
	s_nop 1
	v_permlane16_swap_b32_e32 v131, v6
	v_add_f32_e32 v6, v131, v6
	v_mov_b32_e32 v7, v6
	s_nop 1
	v_permlane32_swap_b32_e32 v6, v7
	v_add_f32_e32 v6, v6, v7
	v_div_scale_f32 v7, s[0:1], v6, v6, 1.0
	v_rcp_f32_e32 v10, v7
	v_permlane16_swap_b32_e32 v0, v2
	v_permlane16_swap_b32_e32 v1, v3
	global_store_dwordx4 v[8:9], v[0:3], off offset:64 nt
	s_add_i32 s26, s26, s90
	s_cmpk_gt_i32 s26, 0x5ff
	v_fma_f32 v0, -v7, v10, 1.0
	v_fmac_f32_e32 v10, v0, v10
	v_div_scale_f32 v0, vcc, 1.0, v6, 1.0
	v_mul_f32_e32 v1, v0, v10
	v_fma_f32 v2, -v7, v1, v0
	v_fmac_f32_e32 v1, v2, v10
	v_fma_f32 v0, -v7, v1, v0
	v_div_fmas_f32 v0, v0, v10, v1
	v_div_fixup_f32 v6, v0, v6, 1.0
	v_pk_mul_f32 v[0:1], v[40:41], v[6:7] op_sel_hi:[1,0]
	v_pk_mul_f32 v[2:3], v[42:43], v[6:7] op_sel_hi:[1,0]
	v_cvt_pk_bf16_f32 v0, v0, v1
	v_cvt_pk_bf16_f32 v1, v2, v3
	v_pk_mul_f32 v[2:3], v[48:49], v[6:7] op_sel_hi:[1,0]
	v_pk_mul_f32 v[8:9], v[50:51], v[6:7] op_sel_hi:[1,0]
	v_cvt_pk_bf16_f32 v2, v2, v3
	v_cvt_pk_bf16_f32 v3, v8, v9
	s_nop 0
	v_permlane16_swap_b32_e32 v0, v2
	v_permlane16_swap_b32_e32 v1, v3
	global_store_dwordx4 v[4:5], v[0:3], off nt
	s_nop 1
	v_pk_mul_f32 v[0:1], v[36:37], v[6:7] op_sel_hi:[1,0]
	v_pk_mul_f32 v[2:3], v[38:39], v[6:7] op_sel_hi:[1,0]
	v_cvt_pk_bf16_f32 v0, v0, v1
	v_cvt_pk_bf16_f32 v1, v2, v3
	v_pk_mul_f32 v[2:3], v[32:33], v[6:7] op_sel_hi:[1,0]
	v_pk_mul_f32 v[6:7], v[34:35], v[6:7] op_sel_hi:[1,0]
	v_cvt_pk_bf16_f32 v2, v2, v3
	v_cvt_pk_bf16_f32 v3, v6, v7
	s_nop 0
	v_permlane16_swap_b32_e32 v0, v2
	v_permlane16_swap_b32_e32 v1, v3
	global_store_dwordx4 v[4:5], v[0:3], off offset:64 nt
	s_cbranch_scc1 .LBB0_1080

.LBB0_1082:
	v_cndmask_b32_e64 v0, v0, v91, s[36:37]
	v_sub_f32_e32 v0, 0, v0
	v_fmamk_f32 v1, v68, 0x3e38aa3b, v0
	v_exp_f32_e32 v1, v1
	v_fmamk_f32 v3, v69, 0x3e38aa3b, v0
	v_exp_f32_e32 v3, v3
	v_fmamk_f32 v13, v70, 0x3e38aa3b, v0
	v_exp_f32_e32 v13, v13
	v_fmamk_f32 v14, v71, 0x3e38aa3b, v0
	v_exp_f32_e32 v14, v14
	v_fmamk_f32 v15, v64, 0x3e38aa3b, v0
	v_fmamk_f32 v64, v65, 0x3e38aa3b, v0
	v_add_f32_e32 v2, 0, v1
	v_exp_f32_e32 v15, v15
	v_exp_f32_e32 v64, v64
	v_add_f32_e32 v2, v3, v2
	v_cndmask_b32_e32 v12, v12, v80, vcc
	v_add_f32_e32 v2, v13, v2
	v_fmamk_f32 v65, v66, 0x3e38aa3b, v0
	v_fmamk_f32 v8, v8, 0x3e38aa3b, v0
	v_sub_f32_e32 v12, 0, v12
	v_add_f32_e32 v2, v14, v2
	v_exp_f32_e32 v65, v65
	v_fmamk_f32 v66, v67, 0x3e38aa3b, v0
	v_exp_f32_e32 v68, v8
	v_fmamk_f32 v8, v9, 0x3e38aa3b, v0
	v_cvt_pk_bf16_f32 v9, v13, v14
	v_fmamk_f32 v13, v56, 0x3e38aa3b, v12
	v_add_f32_e32 v2, v15, v2
	v_exp_f32_e32 v66, v66
	v_fmamk_f32 v60, v60, 0x3e38aa3b, v0
	v_exp_f32_e32 v69, v8
	v_fmamk_f32 v8, v10, 0x3e38aa3b, v0
	v_cvt_pk_bf16_f32 v10, v15, v64
	v_exp_f32_e32 v13, v13
	v_fmamk_f32 v15, v57, 0x3e38aa3b, v12
	v_exp_f32_e32 v67, v60
	v_fmamk_f32 v60, v61, 0x3e38aa3b, v0
	v_exp_f32_e32 v15, v15
	v_fmamk_f32 v56, v58, 0x3e38aa3b, v12
	v_add_f32_e32 v2, v64, v2
	v_exp_f32_e32 v61, v60
	v_fmamk_f32 v60, v62, 0x3e38aa3b, v0
	v_exp_f32_e32 v56, v56
	v_fmamk_f32 v57, v59, 0x3e38aa3b, v12
	v_add_f32_e32 v2, v65, v2
	v_exp_f32_e32 v62, v60
	v_fmamk_f32 v60, v63, 0x3e38aa3b, v0
	v_exp_f32_e32 v57, v57
	v_fmamk_f32 v24, v24, 0x3e38aa3b, v12
	v_add_f32_e32 v2, v66, v2
	v_exp_f32_e32 v63, v60
	v_add_f32_e32 v14, 0, v13
	v_exp_f32_e32 v58, v24
	v_fmamk_f32 v24, v25, 0x3e38aa3b, v12
	v_add_f32_e32 v2, v67, v2
	v_add_f32_e32 v14, v15, v14
	v_exp_f32_e32 v25, v24
	v_fmamk_f32 v24, v26, 0x3e38aa3b, v12
	v_add_f32_e32 v2, v61, v2
	v_add_f32_e32 v14, v56, v14
	v_exp_f32_e32 v26, v24
	v_fmamk_f32 v24, v27, 0x3e38aa3b, v12
	v_add_f32_e32 v2, v62, v2
	v_exp_f32_e32 v70, v8
	v_fmac_f32_e32 v0, 0x3e38aa3b, v11
	v_add_f32_e32 v14, v57, v14
	v_exp_f32_e32 v27, v24
	v_fmamk_f32 v24, v28, 0x3e38aa3b, v12
	v_add_f32_e32 v2, v63, v2
	v_exp_f32_e32 v71, v0
	v_add_f32_e32 v14, v58, v14
	v_exp_f32_e32 v28, v24
	v_fmamk_f32 v24, v29, 0x3e38aa3b, v12
	v_add_f32_e32 v2, v68, v2
	v_add_f32_e32 v14, v25, v14
	v_exp_f32_e32 v29, v24
	v_fmamk_f32 v24, v30, 0x3e38aa3b, v12
	v_add_f32_e32 v2, v69, v2
	v_add_f32_e32 v14, v26, v14
	v_exp_f32_e32 v30, v24
	v_fmamk_f32 v24, v31, 0x3e38aa3b, v12
	v_add_f32_e32 v2, v70, v2
	v_add_f32_e32 v14, v27, v14
	v_exp_f32_e32 v31, v24
	v_fmamk_f32 v4, v4, 0x3e38aa3b, v12
	v_add_f32_e32 v0, v71, v2
	v_add_f32_e32 v14, v28, v14
	v_exp_f32_e32 v59, v4
	v_fmamk_f32 v5, v5, 0x3e38aa3b, v12
	v_add_f32_e32 v60, v0, v81
	v_cvt_pk_bf16_f32 v0, v67, v61
	v_add_f32_e32 v14, v29, v14
	v_exp_f32_e32 v61, v5
	v_fmamk_f32 v5, v6, 0x3e38aa3b, v12
	v_cvt_pk_bf16_f32 v8, v1, v3
	v_cvt_pk_bf16_f32 v1, v62, v63
	v_add_f32_e32 v14, v30, v14
	v_exp_f32_e32 v62, v5
	v_fmac_f32_e32 v12, 0x3e38aa3b, v7
	v_add_f32_e32 v14, v31, v14
	v_exp_f32_e32 v7, v12
	v_add_f32_e32 v4, v59, v14
	v_add_f32_e32 v4, v61, v4
	v_add_f32_e32 v4, v62, v4
	v_add_f32_e32 v24, v7, v4
	v_cvt_pk_bf16_f32 v12, v13, v15
	v_cvt_pk_bf16_f32 v15, v26, v27
	v_cvt_pk_bf16_f32 v4, v28, v29
	v_cvt_pk_bf16_f32 v5, v30, v31
	ds_read_b64_tr_b16 v[28:29], v119 offset:29952
	ds_read_b64_tr_b16 v[26:27], v119 offset:27648
	ds_read_b64_tr_b16 v[30:31], v119 offset:27680
	v_cvt_pk_bf16_f32 v11, v65, v66
	v_cvt_pk_bf16_f32 v13, v56, v57
	v_cvt_pk_bf16_f32 v14, v58, v25
	v_cvt_pk_bf16_f32 v6, v59, v61
	s_waitcnt lgkmcnt(1)
	v_mfma_f32_16x16x32_bf16 v[56:59], v[26:29], v[8:11], v[32:35]
	v_cvt_pk_bf16_f32 v2, v68, v69
	v_cvt_pk_bf16_f32 v3, v70, v71
	v_cvt_pk_bf16_f32 v7, v62, v7
	ds_read_b64_tr_b16 v[32:33], v119 offset:29984
	v_mfma_f32_16x16x32_bf16 v[26:29], v[26:29], v[12:15], v[36:39]
	s_lshl_b64 s[0:1], s[0:1], 11
	s_add_u32 s0, s70, s0
	s_addc_u32 s1, s71, s1
	s_waitcnt lgkmcnt(0)
	v_mfma_f32_16x16x32_bf16 v[34:37], v[30:33], v[8:11], v[48:51]
	s_nop 2
	ds_read_b64_tr_b16 v[48:49], v119 offset:27712
	ds_read_b64_tr_b16 v[50:51], v119 offset:30016
	s_add_u32 s0, s0, s2
	s_addc_u32 s1, s1, 0
	s_waitcnt lgkmcnt(0)
	v_mfma_f32_16x16x32_bf16 v[38:41], v[48:51], v[8:11], v[40:43]
	v_mov_b32_e32 v109, v153
	v_mov_b32_e32 v111, v153
	v_mov_b32_e32 v115, v153
	v_mfma_f32_16x16x32_bf16 v[42:45], v[48:51], v[12:15], v[44:47]
	s_nop 2
	ds_read_b64_tr_b16 v[46:47], v119 offset:27744
	ds_read_b64_tr_b16 v[48:49], v119 offset:30048
	v_mov_b32_e32 v117, v153
	s_add_i32 s13, s13, s90
	v_mfma_f32_16x16x32_bf16 v[30:33], v[30:33], v[12:15], v[52:55]
	s_add_i32 s12, s12, s25
	s_cmpk_lt_i32 s13, 0x200
	s_waitcnt lgkmcnt(0)
	v_mfma_f32_16x16x32_bf16 v[50:53], v[46:49], v[8:11], v[16:19]
	ds_read_b64_tr_b16 v[8:9], v119 offset:32256
	ds_read_b64_tr_b16 v[10:11], v119 offset:34560
	v_mfma_f32_16x16x32_bf16 v[20:23], v[46:49], v[12:15], v[20:23]
	ds_read_b64_tr_b16 v[12:13], v119 offset:32288
	ds_read_b64_tr_b16 v[14:15], v119 offset:34592
	ds_read_b64_tr_b16 v[16:17], v119 offset:32320
	ds_read_b64_tr_b16 v[18:19], v119 offset:34624
	s_waitcnt lgkmcnt(4)
	v_mfma_f32_16x16x32_bf16 v[46:49], v[8:11], v[0:3], v[56:59]
	v_mfma_f32_16x16x32_bf16 v[8:11], v[8:11], v[4:7], v[26:29]
	s_waitcnt lgkmcnt(2)
	v_mfma_f32_16x16x32_bf16 v[26:29], v[12:15], v[0:3], v[34:37]
	s_nop 2
	ds_read_b64_tr_b16 v[34:35], v119 offset:32352
	ds_read_b64_tr_b16 v[36:37], v119 offset:34656
	v_mfma_f32_16x16x32_bf16 v[12:15], v[12:15], v[4:7], v[30:33]
	s_waitcnt lgkmcnt(2)
	v_mfma_f32_16x16x32_bf16 v[30:33], v[16:19], v[0:3], v[38:41]
	v_mfma_f32_16x16x32_bf16 v[16:19], v[16:19], v[4:7], v[42:45]
	s_waitcnt lgkmcnt(0)
	v_mfma_f32_16x16x32_bf16 v[4:7], v[34:37], v[4:7], v[20:23]
	s_nop 2
	v_lshl_add_u64 v[20:21], s[0:1], 0, v[108:109]
	v_mfma_f32_16x16x32_bf16 v[0:3], v[34:37], v[0:3], v[50:53]
	v_add_f32_e32 v35, v24, v72
	v_lshl_add_u64 v[24:25], v[20:21], 0, v[110:111]
	v_mov_b32_e32 v20, v60
	s_nop 1
	v_permlane16_swap_b32_e32 v60, v20
	v_add_f32_e32 v20, v60, v20
	v_mov_b32_e32 v21, v20
	s_nop 1
	v_permlane32_swap_b32_e32 v20, v21
	v_add_f32_e32 v20, v20, v21
	v_div_scale_f32 v21, s[0:1], v20, v20, 1.0
	v_rcp_f32_e32 v22, v21
	s_nop 0
	v_fma_f32 v23, -v21, v22, 1.0
	v_fmac_f32_e32 v22, v23, v22
	v_div_scale_f32 v23, vcc, 1.0, v20, 1.0
	v_mul_f32_e32 v34, v23, v22
	v_fma_f32 v36, -v21, v34, v23
	v_fmac_f32_e32 v34, v36, v22
	v_fma_f32 v21, -v21, v34, v23
	v_div_fmas_f32 v21, v21, v22, v34
	v_div_fixup_f32 v34, v21, v20, 1.0
	v_pk_mul_f32 v[20:21], v[46:47], v[34:35] op_sel_hi:[1,0]
	v_pk_mul_f32 v[22:23], v[48:49], v[34:35] op_sel_hi:[1,0]
	v_cvt_pk_bf16_f32 v20, v20, v21
	v_cvt_pk_bf16_f32 v21, v22, v23
	v_pk_mul_f32 v[22:23], v[26:27], v[34:35] op_sel_hi:[1,0]
	v_pk_mul_f32 v[26:27], v[28:29], v[34:35] op_sel_hi:[1,0]
	v_cvt_pk_bf16_f32 v22, v22, v23
	v_cvt_pk_bf16_f32 v23, v26, v27
	v_lshl_add_u64 v[36:37], v[24:25], 0, v[114:115]
	v_permlane16_swap_b32_e32 v20, v22
	v_permlane16_swap_b32_e32 v21, v23
	global_store_dwordx4 v[36:37], v[20:23], off offset:1536 nt
	v_pk_mul_f32 v[0:1], v[0:1], v[34:35] op_sel_hi:[1,0]
	s_nop 0
	v_pk_mul_f32 v[20:21], v[30:31], v[34:35] op_sel_hi:[1,0]
	v_pk_mul_f32 v[22:23], v[32:33], v[34:35] op_sel_hi:[1,0]
	v_cvt_pk_bf16_f32 v20, v20, v21
	v_cvt_pk_bf16_f32 v21, v22, v23
	v_cvt_pk_bf16_f32 v22, v0, v1
	v_pk_mul_f32 v[0:1], v[2:3], v[34:35] op_sel_hi:[1,0]
	s_nop 0
	v_permlane16_swap_b32_e32 v20, v22
	v_cvt_pk_bf16_f32 v23, v0, v1
	v_mov_b32_e32 v0, v35
	s_nop 1
	v_permlane16_swap_b32_e32 v35, v0
	v_add_f32_e32 v0, v35, v0
	v_mov_b32_e32 v1, v0
	s_nop 1
	v_permlane32_swap_b32_e32 v0, v1
	v_add_f32_e32 v0, v0, v1
	v_div_scale_f32 v1, s[0:1], v0, v0, 1.0
	v_rcp_f32_e32 v2, v1
	v_permlane16_swap_b32_e32 v21, v23
	global_store_dwordx4 v[36:37], v[20:23], off offset:1600 nt
	v_fma_f32 v3, -v1, v2, 1.0
	v_fmac_f32_e32 v2, v3, v2
	v_div_scale_f32 v3, vcc, 1.0, v0, 1.0
	v_mul_f32_e32 v20, v3, v2
	v_fma_f32 v21, -v1, v20, v3
	v_fmac_f32_e32 v20, v21, v2
	v_fma_f32 v1, -v1, v20, v3
	v_div_fmas_f32 v1, v1, v2, v20
	v_div_fixup_f32 v20, v1, v0, 1.0
	v_pk_mul_f32 v[0:1], v[8:9], v[20:21] op_sel_hi:[1,0]
	v_pk_mul_f32 v[2:3], v[10:11], v[20:21] op_sel_hi:[1,0]
	v_cvt_pk_bf16_f32 v0, v0, v1
	v_cvt_pk_bf16_f32 v1, v2, v3
	v_pk_mul_f32 v[2:3], v[12:13], v[20:21] op_sel_hi:[1,0]
	v_pk_mul_f32 v[8:9], v[14:15], v[20:21] op_sel_hi:[1,0]
	v_cvt_pk_bf16_f32 v2, v2, v3
	v_cvt_pk_bf16_f32 v3, v8, v9
	v_lshl_add_u64 v[22:23], v[24:25], 0, v[116:117]
	v_permlane16_swap_b32_e32 v0, v2
	v_permlane16_swap_b32_e32 v1, v3
	global_store_dwordx4 v[22:23], v[0:3], off offset:1536 nt
	s_nop 1
	v_pk_mul_f32 v[0:1], v[16:17], v[20:21] op_sel_hi:[1,0]
	v_pk_mul_f32 v[2:3], v[18:19], v[20:21] op_sel_hi:[1,0]
	v_cvt_pk_bf16_f32 v0, v0, v1
	v_cvt_pk_bf16_f32 v1, v2, v3
	v_pk_mul_f32 v[2:3], v[4:5], v[20:21] op_sel_hi:[1,0]
	v_pk_mul_f32 v[4:5], v[6:7], v[20:21] op_sel_hi:[1,0]
	v_cvt_pk_bf16_f32 v2, v2, v3
	v_cvt_pk_bf16_f32 v3, v4, v5
	s_nop 0
	v_permlane16_swap_b32_e32 v0, v2
	v_permlane16_swap_b32_e32 v1, v3
	global_store_dwordx4 v[22:23], v[0:3], off offset:1600 nt
	s_cbranch_scc0 .LBB0_1095

.LBB0_1238:
	s_add_u32 s12, s88, s0
	s_waitcnt vmcnt(0)
	v_lshl_add_u64 v[14:15], s[88:89], 0, v[4:5]
	s_addc_u32 s13, s89, s1
	v_add_co_u32_e32 v38, vcc, s10, v14
	global_load_dwordx4 v[10:13], v[2:3], off
	s_nop 0
	v_addc_co_u32_e32 v39, vcc, 0, v15, vcc
	global_load_dwordx4 v[14:17], v0, s[12:13]
	global_load_dwordx4 v[18:21], v[38:39], off
	s_add_u32 s12, s12, 0x1f000000
	s_addc_u32 s13, s13, 0
	global_load_dwordx4 v[22:25], v1, s[12:13] offset:16
	global_load_dwordx4 v[26:29], v1, s[12:13] offset:32
	global_load_dwordx4 v[30:33], v1, s[12:13] offset:48
	global_load_dwordx4 v[34:37], v[2:3], off offset:16
	s_add_i32 s8, s8, s14
	s_add_u32 s0, s0, s2
	s_addc_u32 s1, s1, s3
	v_lshl_add_u64 v[4:5], v[4:5], 0, s[4:5]
	s_cmp_lt_i32 s8, 0x8000
	s_waitcnt vmcnt(5)
	v_mov_b32_e32 v40, v15
	v_mov_b32_e32 v41, v16
	v_mov_b32_e32 v15, v17
	v_pk_add_f32 v[14:15], v[40:41], v[14:15]
	s_waitcnt vmcnt(3)
	v_mov_b32_e32 v40, v23
	v_mov_b32_e32 v41, v24
	v_mov_b32_e32 v23, v25
	v_pk_add_f32 v[22:23], v[40:41], v[22:23]
	v_pk_add_f32 v[14:15], v[14:15], v[14:15] op_sel:[0,1] op_sel_hi:[1,0]
	v_pk_add_f32 v[22:23], v[22:23], v[22:23] op_sel:[0,1] op_sel_hi:[1,0]
	s_waitcnt vmcnt(2)
	v_add_f32_e32 v24, v26, v27
	v_add_f32_e32 v26, v28, v29
	s_waitcnt vmcnt(1)
	v_mov_b32_e32 v25, v32
	v_mov_b32_e32 v27, v33
	v_mov_b32_e32 v15, v30
	v_mov_b32_e32 v23, v31
	v_pk_add_f32 v[24:25], v[24:25], v[26:27]
	v_pk_add_f32 v[14:15], v[14:15], v[22:23]
	v_lshlrev_b32_e32 v16, 16, v18
	v_pk_add_f32 v[14:15], v[14:15], v[24:25]
	v_and_b32_e32 v17, 0xffff0000, v18
	v_add_f32_e32 v9, v14, v15
	v_fmamk_f32 v9, v9, 0x3a800000, v8
	v_mul_f32_e32 v14, 0x4b800000, v9
	v_cmp_gt_f32_e32 vcc, s9, v9
	v_lshlrev_b32_e32 v18, 16, v19
	v_and_b32_e32 v19, 0xffff0000, v19
	v_cndmask_b32_e32 v9, v9, v14, vcc
	v_rsq_f32_e32 v9, v9
	v_lshlrev_b32_e32 v42, 16, v20
	v_and_b32_e32 v43, 0xffff0000, v20
	v_lshlrev_b32_e32 v20, 16, v21
	v_mul_f32_e32 v14, 0x45800000, v9
	v_cndmask_b32_e32 v22, v9, v14, vcc
	v_and_b32_e32 v21, 0xffff0000, v21
	v_pk_mul_f32 v[14:15], v[22:23], v[16:17] op_sel_hi:[0,1]
	v_pk_mul_f32 v[16:17], v[22:23], v[18:19] op_sel_hi:[0,1]
	v_pk_mul_f32 v[18:19], v[22:23], v[42:43] op_sel_hi:[0,1]
	v_pk_mul_f32 v[20:21], v[22:23], v[20:21] op_sel_hi:[0,1]
	v_pk_mul_f32 v[10:11], v[10:11], v[14:15]
	v_pk_mul_f32 v[12:13], v[12:13], v[16:17]
	s_waitcnt vmcnt(0)
	v_pk_mul_f32 v[14:15], v[34:35], v[18:19]
	v_pk_mul_f32 v[16:17], v[36:37], v[20:21]
	global_store_dwordx4 v[6:7], v[10:13], off offset:-2064 nt
	global_store_dwordx4 v[6:7], v[14:17], off offset:-2048 nt
	global_load_dwordx4 v[10:13], v[38:39], off offset:1024
	s_nop 0
	global_load_dwordx4 v[14:17], v[2:3], off offset:2048
	global_load_dwordx4 v[18:21], v[2:3], off offset:2064
	s_waitcnt vmcnt(2)
	v_lshlrev_b32_e32 v24, 16, v10
	v_and_b32_e32 v25, 0xffff0000, v10
	v_lshlrev_b32_e32 v10, 16, v11
	v_and_b32_e32 v11, 0xffff0000, v11
	v_lshlrev_b32_e32 v26, 16, v12
	v_and_b32_e32 v27, 0xffff0000, v12
	v_lshlrev_b32_e32 v12, 16, v13
	v_and_b32_e32 v13, 0xffff0000, v13
	v_pk_mul_f32 v[24:25], v[22:23], v[24:25] op_sel_hi:[0,1]
	v_pk_mul_f32 v[28:29], v[22:23], v[10:11] op_sel_hi:[0,1]
	v_pk_mul_f32 v[26:27], v[22:23], v[26:27] op_sel_hi:[0,1]
	v_pk_mul_f32 v[22:23], v[22:23], v[12:13] op_sel_hi:[0,1]
	s_waitcnt vmcnt(1)
	v_pk_mul_f32 v[10:11], v[14:15], v[24:25]
	v_pk_mul_f32 v[12:13], v[16:17], v[28:29]
	s_waitcnt vmcnt(0)
	v_pk_mul_f32 v[14:15], v[18:19], v[26:27]
	v_pk_mul_f32 v[16:17], v[20:21], v[22:23]
	global_store_dwordx4 v[6:7], v[10:13], off offset:-16 nt
	global_store_dwordx4 v[6:7], v[14:17], off nt
	v_lshl_add_u64 v[6:7], v[6:7], 0, s[6:7]
	s_cbranch_scc1 .LBB0_1238
